# Fourier layers: special-row channel-DFT GEMV loop (8 workgroups) software-pipelined, 4 iterations of weight loads in flight via x4 unroll with rotating register sets; its three serial input loads batc
# speedup vs baseline: 1.0071x; 1.0071x over previous
.LBB0_271:
	s_or_b64 exec, exec, s[46:47]
	v_readlane_b32 s4, v255, 7
	s_lshr_b32 s46, s85, 1
	v_readlane_b32 s5, v255, 8
	s_and_b64 s[4:5], s[4:5], exec
	v_readlane_b32 s6, v255, 5
	s_cselect_b32 s84, 0, 0x100
	v_readlane_b32 s7, v255, 6
	v_writelane_b32 v255, s85, 11
	s_mov_b64 s[4:5], -1
	s_and_b64 vcc, exec, s[6:7]
	v_writelane_b32 v255, s84, 12
	s_waitcnt lgkmcnt(0)
	s_barrier
	s_cbranch_vccz .LBB0_656
	v_readlane_b32 s4, v254, 14
	v_readlane_b32 s5, v254, 15
	s_andn2_b64 vcc, exec, s[4:5]
	s_cbranch_vccnz .LBB0_280
	v_mbcnt_lo_u32_b32 v0, -1, 0
	v_mbcnt_hi_u32_b32 v0, -1, v0
	v_readlane_b32 s2, v254, 46
	s_nop 1
	v_add_u32_e32 v0, s2, v0
	s_movk_i32 s2, 0x100
	v_cmp_gt_i32_e64 s[6:7], s2, v0
	v_readlane_b32 s2, v254, 17
	s_nop 1
	v_add_u32_e32 v22, s2, v0
	v_readlane_b32 s2, v254, 16
	v_ashrrev_i32_e32 v23, 31, v22
	s_nop 0
	v_add_u32_e32 v20, s2, v0
	v_readlane_b32 s2, v254, 18
	v_ashrrev_i32_e32 v21, 31, v20
	s_nop 0
	v_add_u32_e32 v18, s2, v0
	v_ashrrev_i32_e32 v19, 31, v18
	s_and_saveexec_b64 s[8:9], s[6:7]
	s_cbranch_execz .LBB0_275
	s_mov_b64 s[4:5], s[0:1]
	s_load_dwordx2 s[4:5], s[4:5], 0xa8
	v_lshl_add_u32 v4, v0, 2, 0
	s_waitcnt lgkmcnt(0)
	v_lshl_add_u64 v[2:3], v[22:23], 2, s[4:5]
	v_add_co_u32_e32 v2, vcc, 0x58400000, v2
	s_mov_b64 s[4:5], s[0:1]
	s_nop 0
	v_addc_co_u32_e32 v3, vcc, 0, v3, vcc
	global_load_dword v1, v[2:3], off
	s_load_dwordx2 s[4:5], s[4:5], 0xa8
	s_waitcnt lgkmcnt(0)
	v_lshl_add_u64 v[2:3], v[20:21], 2, s[4:5]
	v_add_co_u32_e32 v2, vcc, 0x58400000, v2
	s_mov_b64 s[4:5], s[0:1]
	s_nop 0
	v_addc_co_u32_e32 v3, vcc, 0, v3, vcc
	global_load_dword v5, v[2:3], off
	s_load_dwordx2 s[4:5], s[4:5], 0xa8
	s_waitcnt lgkmcnt(0)
	v_lshl_add_u64 v[2:3], v[18:19], 2, s[4:5]
	v_add_co_u32_e32 v2, vcc, 0x58400000, v2
	s_nop 1
	v_addc_co_u32_e32 v3, vcc, 0, v3, vcc
	global_load_dword v6, v[2:3], off
	s_waitcnt vmcnt(0)
	ds_write_b32 v4, v1
	ds_write_b32 v4, v5 offset:1024
	ds_write_b32 v4, v6 offset:2048
.LBB0_275:
	s_or_b64 exec, exec, s[8:9]
	s_waitcnt lgkmcnt(0)
	s_barrier
	s_and_saveexec_b64 s[8:9], s[6:7]
	s_cbranch_execz .LBB0_279
	s_mov_b64 s[4:5], s[0:1]
	s_mov_b64 s[6:7], s[0:1]
	s_load_dwordx2 s[4:5], s[4:5], 0xa8
	s_load_dwordx2 s[6:7], s[6:7], 0xa8
	v_ashrrev_i32_e32 v1, 31, v0
	v_lshlrev_b64 v[0:1], 9, v[0:1]
	s_waitcnt lgkmcnt(0)
	v_lshl_add_u64 v[2:3], s[4:5], 0, v[0:1]
	s_mov_b64 s[4:5], 0x400010
	v_lshl_add_u64 v[24:25], v[2:3], 0, s[4:5]
	v_lshl_add_u64 v[0:1], s[6:7], 0, v[0:1]
	s_mov_b64 s[4:5], 0x420010
	v_mov_b32_e32 v8, 0
	v_lshl_add_u64 v[26:27], v[0:1], 0, s[4:5]
	s_mov_b32 s2, -8
	s_mov_b32 s4, 0
	v_mov_b32_e32 v28, 0
	v_mov_b32_e32 v29, v8
	global_load_dwordx4 v[124:127], v[24:25], off
	global_load_dwordx4 v[128:131], v[24:25], off offset:-16
	global_load_dwordx4 v[132:135], v[26:27], off
	global_load_dwordx4 v[136:139], v[26:27], off offset:-16
	global_load_dwordx4 v[140:143], v[24:25], off offset:32
	global_load_dwordx4 v[144:147], v[24:25], off offset:16
	global_load_dwordx4 v[148:151], v[26:27], off offset:32
	global_load_dwordx4 v[152:155], v[26:27], off offset:16
	global_load_dwordx4 v[156:159], v[24:25], off offset:64
	global_load_dwordx4 v[160:163], v[24:25], off offset:48
	global_load_dwordx4 v[164:167], v[26:27], off offset:64
	global_load_dwordx4 v[168:171], v[26:27], off offset:48
	global_load_dwordx4 v[60:63], v[24:25], off offset:96
	global_load_dwordx4 v[64:67], v[24:25], off offset:80
	global_load_dwordx4 v[68:71], v[26:27], off offset:96
	global_load_dwordx4 v[72:75], v[26:27], off offset:80
.LBB0_277:
	s_waitcnt vmcnt(12)
	v_mov_b64_e32 v[4:5], v[124:125]
	v_mov_b64_e32 v[6:7], v[126:127]
	v_mov_b64_e32 v[32:33], v[128:129]
	v_mov_b64_e32 v[34:35], v[130:131]
	v_mov_b64_e32 v[0:1], v[132:133]
	v_mov_b64_e32 v[2:3], v[134:135]
	v_mov_b64_e32 v[14:15], v[136:137]
	v_mov_b64_e32 v[16:17], v[138:139]
	v_mov_b32_e32 v30, s4
	ds_read_b96 v[10:12], v30 offset:2048
	s_add_i32 s5, s4, 0x80c
	s_add_i32 s2, s2, 16
	v_lshl_add_u64 v[24:25], v[24:25], 0, 32
	v_lshl_add_u64 v[26:27], v[26:27], 0, 32
	global_load_dwordx4 v[124:127], v[24:25], off offset:96
	global_load_dwordx4 v[128:131], v[24:25], off offset:80
	global_load_dwordx4 v[132:135], v[26:27], off offset:96
	global_load_dwordx4 v[136:139], v[26:27], off offset:80
	v_and_b32_e32 v49, 0xffff0000, v32
	v_and_b32_e32 v48, 16, v32
	v_lshlrev_b32_e32 v36, 16, v14
	v_and_b32_e32 v37, 0xffff0000, v14
	s_waitcnt lgkmcnt(0)
	v_pk_mul_f32 v[10:11], v[10:11], v[36:37]
	v_lshlrev_b32_e32 v14, 16, v15
	v_add_f32_e32 v9, v10, v11
	v_add_f32_e32 v13, v8, v9
	ds_read_b32 v9, v30 offset:2068
	v_mov_b32_e32 v8, s5
	ds_read2_b32 v[36:37], v8 offset1:1
	v_and_b32_e32 v10, 0xffff0000, v15
	v_and_b32_e32 v15, 0xffff0000, v16
	v_mov_b32_e32 v8, v12
	v_lshlrev_b32_e32 v11, 16, v16
	s_waitcnt lgkmcnt(1)
	v_pk_mul_f32 v[8:9], v[8:9], v[14:15]
	v_lshlrev_b32_e32 v50, 16, v32
	s_waitcnt lgkmcnt(0)
	v_pk_fma_f32 v[8:9], v[36:37], v[10:11], v[8:9]
	v_mov_b32_e32 v51, v49
	v_add_f32_e32 v8, v13, v8
	v_add_f32_e32 v31, v8, v9
	ds_read_b128 v[36:39], v30
	ds_read_b128 v[40:43], v30 offset:16
	ds_read_b128 v[12:15], v30 offset:32
	ds_read_b128 v[8:11], v30 offset:48
	ds_read_b128 v[44:47], v30 offset:1024
	s_waitcnt lgkmcnt(4)
	v_mov_b32_e32 v53, v37
	v_lshlrev_b32_e32 v32, 16, v33
	s_add_i32 s5, s4, 0x818
	v_lshlrev_b32_e32 v16, 16, v17
	s_waitcnt lgkmcnt(0)
	v_mov_b32_e32 v52, v44
	v_mov_b32_e32 v44, v45
	v_mov_b32_e32 v45, v36
	v_pk_mov_b32 v[36:37], v[48:49], v[50:51] op_sel:[1,0]
	v_and_b32_e32 v17, 0xffff0000, v17
	v_pk_mul_f32 v[36:37], v[44:45], v[36:37]
	v_mov_b32_e32 v44, v46
	v_pk_fma_f32 v[36:37], v[52:53], v[50:51], v[36:37]
	v_mov_b32_e32 v46, v47
	v_pk_add_f32 v[28:29], v[28:29], v[36:37]
	v_and_b32_e32 v37, 0xffff0000, v33
	v_and_b32_e32 v36, 16, v33
	v_mov_b32_e32 v33, v37
	v_mov_b32_e32 v47, v38
	v_pk_mov_b32 v[36:37], v[36:37], v[32:33] op_sel:[1,0]
	v_mov_b32_e32 v45, v39
	v_pk_mul_f32 v[36:37], v[46:47], v[36:37]
	v_mov_b32_e32 v47, v41
	v_pk_fma_f32 v[32:33], v[44:45], v[32:33], v[36:37]
	ds_read_b128 v[36:39], v30 offset:1040
	v_pk_add_f32 v[28:29], v[28:29], v[32:33]
	v_and_b32_e32 v33, 0xffff0000, v34
	v_and_b32_e32 v32, 16, v34
	v_lshlrev_b32_e32 v44, 16, v34
	v_mov_b32_e32 v45, v33
	s_waitcnt lgkmcnt(0)
	v_mov_b32_e32 v46, v36
	v_mov_b32_e32 v36, v37
	v_mov_b32_e32 v37, v40
	v_pk_mov_b32 v[32:33], v[32:33], v[44:45] op_sel:[1,0]
	v_lshlrev_b32_e32 v34, 16, v35
	v_pk_mul_f32 v[32:33], v[36:37], v[32:33]
	v_mov_b32_e32 v36, v38
	v_pk_fma_f32 v[32:33], v[46:47], v[44:45], v[32:33]
	v_mov_b32_e32 v38, v39
	v_pk_add_f32 v[28:29], v[28:29], v[32:33]
	v_and_b32_e32 v33, 0xffff0000, v35
	v_and_b32_e32 v32, 16, v35
	v_mov_b32_e32 v35, v33
	v_mov_b32_e32 v39, v42
	v_pk_mov_b32 v[32:33], v[32:33], v[34:35] op_sel:[1,0]
	v_mov_b32_e32 v37, v43
	v_pk_mul_f32 v[32:33], v[38:39], v[32:33]
	s_nop 0
	v_pk_fma_f32 v[32:33], v[36:37], v[34:35], v[32:33]
	v_and_b32_e32 v36, 0xffff0000, v1
	v_pk_add_f32 v[28:29], v[28:29], v[32:33]
	v_mov_b32_e32 v32, s5
	ds_read2_b64 v[32:35], v32 offset1:1
	s_add_i32 s5, s4, 0x828
	v_lshlrev_b32_e32 v37, 16, v2
	s_add_i32 s4, s4, 64
	s_cmpk_gt_u32 s2, 0xf7
	s_waitcnt lgkmcnt(0)
	v_pk_mul_f32 v[16:17], v[32:33], v[16:17]
	s_nop 0
	v_add_f32_e32 v16, v16, v17
	v_add_f32_e32 v31, v31, v16
	v_lshlrev_b32_e32 v16, 16, v0
	v_and_b32_e32 v17, 0xffff0000, v0
	v_pk_mul_f32 v[16:17], v[34:35], v[16:17]
	s_nop 0
	v_add_f32_e32 v0, v16, v17
	v_add_f32_e32 v31, v31, v0
	v_mov_b32_e32 v0, s5
	ds_read2_b64 v[32:35], v0 offset1:1
	v_lshlrev_b32_e32 v0, 16, v1
	v_and_b32_e32 v1, 0xffff0000, v2
	s_waitcnt lgkmcnt(0)
	v_mov_b32_e32 v16, v33
	v_mov_b32_e32 v33, v35
	v_mov_b32_e32 v17, v34
	v_pk_mul_f32 v[0:1], v[32:33], v[0:1]
	ds_read_b128 v[32:35], v30 offset:1056
	v_pk_fma_f32 v[0:1], v[16:17], v[36:37], v[0:1]
	v_lshlrev_b32_e32 v16, 16, v4
	v_add_f32_e32 v0, v31, v0
	v_add_f32_e32 v31, v0, v1
	v_and_b32_e32 v1, 0xffff0000, v4
	v_and_b32_e32 v0, 16, v4
	v_mov_b32_e32 v17, v1
	s_waitcnt lgkmcnt(0)
	v_mov_b32_e32 v36, v32
	v_mov_b32_e32 v32, v33
	v_mov_b32_e32 v33, v12
	v_pk_mov_b32 v[0:1], v[0:1], v[16:17] op_sel:[1,0]
	v_mov_b32_e32 v37, v13
	v_pk_mul_f32 v[0:1], v[32:33], v[0:1]
	v_and_b32_e32 v13, 0xffff0000, v5
	v_pk_fma_f32 v[0:1], v[36:37], v[16:17], v[0:1]
	v_and_b32_e32 v12, 16, v5
	v_lshlrev_b32_e32 v4, 16, v5
	v_mov_b32_e32 v5, v13
	v_pk_add_f32 v[0:1], v[28:29], v[0:1]
	v_mov_b32_e32 v28, v35
	v_mov_b32_e32 v29, v14
	v_pk_mov_b32 v[12:13], v[12:13], v[4:5] op_sel:[1,0]
	v_mov_b32_e32 v16, v34
	v_mov_b32_e32 v17, v15
	v_pk_mul_f32 v[12:13], v[28:29], v[12:13]
	v_mov_b32_e32 v29, v9
	v_pk_fma_f32 v[4:5], v[16:17], v[4:5], v[12:13]
	ds_read_b128 v[12:15], v30 offset:1072
	v_pk_add_f32 v[0:1], v[0:1], v[4:5]
	v_and_b32_e32 v5, 0xffff0000, v6
	v_and_b32_e32 v4, 16, v6
	v_lshlrev_b32_e32 v16, 16, v6
	v_mov_b32_e32 v17, v5
	s_waitcnt lgkmcnt(0)
	v_mov_b32_e32 v28, v12
	v_mov_b32_e32 v12, v13
	v_mov_b32_e32 v13, v8
	v_pk_mov_b32 v[4:5], v[4:5], v[16:17] op_sel:[1,0]
	v_lshlrev_b32_e32 v6, 16, v7
	v_pk_mul_f32 v[4:5], v[12:13], v[4:5]
	v_mov_b32_e32 v12, v15
	v_pk_fma_f32 v[4:5], v[28:29], v[16:17], v[4:5]
	v_mov_b32_e32 v13, v10
	v_pk_add_f32 v[0:1], v[0:1], v[4:5]
	v_and_b32_e32 v5, 0xffff0000, v7
	v_and_b32_e32 v4, 16, v7
	v_mov_b32_e32 v7, v5
	v_pk_mov_b32 v[4:5], v[4:5], v[6:7] op_sel:[1,0]
	v_mov_b32_e32 v8, v14
	v_mov_b32_e32 v9, v11
	v_pk_mul_f32 v[4:5], v[12:13], v[4:5]
	s_nop 0
	v_pk_fma_f32 v[4:5], v[8:9], v[6:7], v[4:5]
	s_nop 0
	v_pk_add_f32 v[28:29], v[0:1], v[4:5]
	v_lshlrev_b32_e32 v0, 16, v3
	v_and_b32_e32 v1, 0xffff0000, v3
	ds_read_b64 v[2:3], v30 offset:2104
	s_waitcnt lgkmcnt(0)
	v_pk_mul_f32 v[0:1], v[2:3], v[0:1]
	s_nop 0
	v_add_f32_e32 v0, v0, v1
	v_add_f32_e32 v8, v31, v0
	s_waitcnt vmcnt(12)
	v_mov_b64_e32 v[4:5], v[140:141]
	v_mov_b64_e32 v[6:7], v[142:143]
	v_mov_b64_e32 v[32:33], v[144:145]
	v_mov_b64_e32 v[34:35], v[146:147]
	v_mov_b64_e32 v[0:1], v[148:149]
	v_mov_b64_e32 v[2:3], v[150:151]
	v_mov_b64_e32 v[14:15], v[152:153]
	v_mov_b64_e32 v[16:17], v[154:155]
	v_mov_b32_e32 v30, s4
	ds_read_b96 v[10:12], v30 offset:2048
	s_add_i32 s5, s4, 0x80c
	s_add_i32 s2, s2, 16
	v_lshl_add_u64 v[24:25], v[24:25], 0, 32
	v_lshl_add_u64 v[26:27], v[26:27], 0, 32
	global_load_dwordx4 v[140:143], v[24:25], off offset:96
	global_load_dwordx4 v[144:147], v[24:25], off offset:80
	global_load_dwordx4 v[148:151], v[26:27], off offset:96
	global_load_dwordx4 v[152:155], v[26:27], off offset:80
	v_and_b32_e32 v49, 0xffff0000, v32
	v_and_b32_e32 v48, 16, v32
	v_lshlrev_b32_e32 v36, 16, v14
	v_and_b32_e32 v37, 0xffff0000, v14
	s_waitcnt lgkmcnt(0)
	v_pk_mul_f32 v[10:11], v[10:11], v[36:37]
	v_lshlrev_b32_e32 v14, 16, v15
	v_add_f32_e32 v9, v10, v11
	v_add_f32_e32 v13, v8, v9
	ds_read_b32 v9, v30 offset:2068
	v_mov_b32_e32 v8, s5
	ds_read2_b32 v[36:37], v8 offset1:1
	v_and_b32_e32 v10, 0xffff0000, v15
	v_and_b32_e32 v15, 0xffff0000, v16
	v_mov_b32_e32 v8, v12
	v_lshlrev_b32_e32 v11, 16, v16
	s_waitcnt lgkmcnt(1)
	v_pk_mul_f32 v[8:9], v[8:9], v[14:15]
	v_lshlrev_b32_e32 v50, 16, v32
	s_waitcnt lgkmcnt(0)
	v_pk_fma_f32 v[8:9], v[36:37], v[10:11], v[8:9]
	v_mov_b32_e32 v51, v49
	v_add_f32_e32 v8, v13, v8
	v_add_f32_e32 v31, v8, v9
	ds_read_b128 v[36:39], v30
	ds_read_b128 v[40:43], v30 offset:16
	ds_read_b128 v[12:15], v30 offset:32
	ds_read_b128 v[8:11], v30 offset:48
	ds_read_b128 v[44:47], v30 offset:1024
	s_waitcnt lgkmcnt(4)
	v_mov_b32_e32 v53, v37
	v_lshlrev_b32_e32 v32, 16, v33
	s_add_i32 s5, s4, 0x818
	v_lshlrev_b32_e32 v16, 16, v17
	s_waitcnt lgkmcnt(0)
	v_mov_b32_e32 v52, v44
	v_mov_b32_e32 v44, v45
	v_mov_b32_e32 v45, v36
	v_pk_mov_b32 v[36:37], v[48:49], v[50:51] op_sel:[1,0]
	v_and_b32_e32 v17, 0xffff0000, v17
	v_pk_mul_f32 v[36:37], v[44:45], v[36:37]
	v_mov_b32_e32 v44, v46
	v_pk_fma_f32 v[36:37], v[52:53], v[50:51], v[36:37]
	v_mov_b32_e32 v46, v47
	v_pk_add_f32 v[28:29], v[28:29], v[36:37]
	v_and_b32_e32 v37, 0xffff0000, v33
	v_and_b32_e32 v36, 16, v33
	v_mov_b32_e32 v33, v37
	v_mov_b32_e32 v47, v38
	v_pk_mov_b32 v[36:37], v[36:37], v[32:33] op_sel:[1,0]
	v_mov_b32_e32 v45, v39
	v_pk_mul_f32 v[36:37], v[46:47], v[36:37]
	v_mov_b32_e32 v47, v41
	v_pk_fma_f32 v[32:33], v[44:45], v[32:33], v[36:37]
	ds_read_b128 v[36:39], v30 offset:1040
	v_pk_add_f32 v[28:29], v[28:29], v[32:33]
	v_and_b32_e32 v33, 0xffff0000, v34
	v_and_b32_e32 v32, 16, v34
	v_lshlrev_b32_e32 v44, 16, v34
	v_mov_b32_e32 v45, v33
	s_waitcnt lgkmcnt(0)
	v_mov_b32_e32 v46, v36
	v_mov_b32_e32 v36, v37
	v_mov_b32_e32 v37, v40
	v_pk_mov_b32 v[32:33], v[32:33], v[44:45] op_sel:[1,0]
	v_lshlrev_b32_e32 v34, 16, v35
	v_pk_mul_f32 v[32:33], v[36:37], v[32:33]
	v_mov_b32_e32 v36, v38
	v_pk_fma_f32 v[32:33], v[46:47], v[44:45], v[32:33]
	v_mov_b32_e32 v38, v39
	v_pk_add_f32 v[28:29], v[28:29], v[32:33]
	v_and_b32_e32 v33, 0xffff0000, v35
	v_and_b32_e32 v32, 16, v35
	v_mov_b32_e32 v35, v33
	v_mov_b32_e32 v39, v42
	v_pk_mov_b32 v[32:33], v[32:33], v[34:35] op_sel:[1,0]
	v_mov_b32_e32 v37, v43
	v_pk_mul_f32 v[32:33], v[38:39], v[32:33]
	s_nop 0
	v_pk_fma_f32 v[32:33], v[36:37], v[34:35], v[32:33]
	v_and_b32_e32 v36, 0xffff0000, v1
	v_pk_add_f32 v[28:29], v[28:29], v[32:33]
	v_mov_b32_e32 v32, s5
	ds_read2_b64 v[32:35], v32 offset1:1
	s_add_i32 s5, s4, 0x828
	v_lshlrev_b32_e32 v37, 16, v2
	s_add_i32 s4, s4, 64
	s_cmpk_gt_u32 s2, 0xf7
	s_waitcnt lgkmcnt(0)
	v_pk_mul_f32 v[16:17], v[32:33], v[16:17]
	s_nop 0
	v_add_f32_e32 v16, v16, v17
	v_add_f32_e32 v31, v31, v16
	v_lshlrev_b32_e32 v16, 16, v0
	v_and_b32_e32 v17, 0xffff0000, v0
	v_pk_mul_f32 v[16:17], v[34:35], v[16:17]
	s_nop 0
	v_add_f32_e32 v0, v16, v17
	v_add_f32_e32 v31, v31, v0
	v_mov_b32_e32 v0, s5
	ds_read2_b64 v[32:35], v0 offset1:1
	v_lshlrev_b32_e32 v0, 16, v1
	v_and_b32_e32 v1, 0xffff0000, v2
	s_waitcnt lgkmcnt(0)
	v_mov_b32_e32 v16, v33
	v_mov_b32_e32 v33, v35
	v_mov_b32_e32 v17, v34
	v_pk_mul_f32 v[0:1], v[32:33], v[0:1]
	ds_read_b128 v[32:35], v30 offset:1056
	v_pk_fma_f32 v[0:1], v[16:17], v[36:37], v[0:1]
	v_lshlrev_b32_e32 v16, 16, v4
	v_add_f32_e32 v0, v31, v0
	v_add_f32_e32 v31, v0, v1
	v_and_b32_e32 v1, 0xffff0000, v4
	v_and_b32_e32 v0, 16, v4
	v_mov_b32_e32 v17, v1
	s_waitcnt lgkmcnt(0)
	v_mov_b32_e32 v36, v32
	v_mov_b32_e32 v32, v33
	v_mov_b32_e32 v33, v12
	v_pk_mov_b32 v[0:1], v[0:1], v[16:17] op_sel:[1,0]
	v_mov_b32_e32 v37, v13
	v_pk_mul_f32 v[0:1], v[32:33], v[0:1]
	v_and_b32_e32 v13, 0xffff0000, v5
	v_pk_fma_f32 v[0:1], v[36:37], v[16:17], v[0:1]
	v_and_b32_e32 v12, 16, v5
	v_lshlrev_b32_e32 v4, 16, v5
	v_mov_b32_e32 v5, v13
	v_pk_add_f32 v[0:1], v[28:29], v[0:1]
	v_mov_b32_e32 v28, v35
	v_mov_b32_e32 v29, v14
	v_pk_mov_b32 v[12:13], v[12:13], v[4:5] op_sel:[1,0]
	v_mov_b32_e32 v16, v34
	v_mov_b32_e32 v17, v15
	v_pk_mul_f32 v[12:13], v[28:29], v[12:13]
	v_mov_b32_e32 v29, v9
	v_pk_fma_f32 v[4:5], v[16:17], v[4:5], v[12:13]
	ds_read_b128 v[12:15], v30 offset:1072
	v_pk_add_f32 v[0:1], v[0:1], v[4:5]
	v_and_b32_e32 v5, 0xffff0000, v6
	v_and_b32_e32 v4, 16, v6
	v_lshlrev_b32_e32 v16, 16, v6
	v_mov_b32_e32 v17, v5
	s_waitcnt lgkmcnt(0)
	v_mov_b32_e32 v28, v12
	v_mov_b32_e32 v12, v13
	v_mov_b32_e32 v13, v8
	v_pk_mov_b32 v[4:5], v[4:5], v[16:17] op_sel:[1,0]
	v_lshlrev_b32_e32 v6, 16, v7
	v_pk_mul_f32 v[4:5], v[12:13], v[4:5]
	v_mov_b32_e32 v12, v15
	v_pk_fma_f32 v[4:5], v[28:29], v[16:17], v[4:5]
	v_mov_b32_e32 v13, v10
	v_pk_add_f32 v[0:1], v[0:1], v[4:5]
	v_and_b32_e32 v5, 0xffff0000, v7
	v_and_b32_e32 v4, 16, v7
	v_mov_b32_e32 v7, v5
	v_pk_mov_b32 v[4:5], v[4:5], v[6:7] op_sel:[1,0]
	v_mov_b32_e32 v8, v14
	v_mov_b32_e32 v9, v11
	v_pk_mul_f32 v[4:5], v[12:13], v[4:5]
	s_nop 0
	v_pk_fma_f32 v[4:5], v[8:9], v[6:7], v[4:5]
	s_nop 0
	v_pk_add_f32 v[28:29], v[0:1], v[4:5]
	v_lshlrev_b32_e32 v0, 16, v3
	v_and_b32_e32 v1, 0xffff0000, v3
	ds_read_b64 v[2:3], v30 offset:2104
	s_waitcnt lgkmcnt(0)
	v_pk_mul_f32 v[0:1], v[2:3], v[0:1]
	s_nop 0
	v_add_f32_e32 v0, v0, v1
	v_add_f32_e32 v8, v31, v0
	s_waitcnt vmcnt(12)
	v_mov_b64_e32 v[4:5], v[156:157]
	v_mov_b64_e32 v[6:7], v[158:159]
	v_mov_b64_e32 v[32:33], v[160:161]
	v_mov_b64_e32 v[34:35], v[162:163]
	v_mov_b64_e32 v[0:1], v[164:165]
	v_mov_b64_e32 v[2:3], v[166:167]
	v_mov_b64_e32 v[14:15], v[168:169]
	v_mov_b64_e32 v[16:17], v[170:171]
	v_mov_b32_e32 v30, s4
	ds_read_b96 v[10:12], v30 offset:2048
	s_add_i32 s5, s4, 0x80c
	s_add_i32 s2, s2, 16
	v_lshl_add_u64 v[24:25], v[24:25], 0, 32
	v_lshl_add_u64 v[26:27], v[26:27], 0, 32
	global_load_dwordx4 v[156:159], v[24:25], off offset:96
	global_load_dwordx4 v[160:163], v[24:25], off offset:80
	global_load_dwordx4 v[164:167], v[26:27], off offset:96
	global_load_dwordx4 v[168:171], v[26:27], off offset:80
	v_and_b32_e32 v49, 0xffff0000, v32
	v_and_b32_e32 v48, 16, v32
	v_lshlrev_b32_e32 v36, 16, v14
	v_and_b32_e32 v37, 0xffff0000, v14
	s_waitcnt lgkmcnt(0)
	v_pk_mul_f32 v[10:11], v[10:11], v[36:37]
	v_lshlrev_b32_e32 v14, 16, v15
	v_add_f32_e32 v9, v10, v11
	v_add_f32_e32 v13, v8, v9
	ds_read_b32 v9, v30 offset:2068
	v_mov_b32_e32 v8, s5
	ds_read2_b32 v[36:37], v8 offset1:1
	v_and_b32_e32 v10, 0xffff0000, v15
	v_and_b32_e32 v15, 0xffff0000, v16
	v_mov_b32_e32 v8, v12
	v_lshlrev_b32_e32 v11, 16, v16
	s_waitcnt lgkmcnt(1)
	v_pk_mul_f32 v[8:9], v[8:9], v[14:15]
	v_lshlrev_b32_e32 v50, 16, v32
	s_waitcnt lgkmcnt(0)
	v_pk_fma_f32 v[8:9], v[36:37], v[10:11], v[8:9]
	v_mov_b32_e32 v51, v49
	v_add_f32_e32 v8, v13, v8
	v_add_f32_e32 v31, v8, v9
	ds_read_b128 v[36:39], v30
	ds_read_b128 v[40:43], v30 offset:16
	ds_read_b128 v[12:15], v30 offset:32
	ds_read_b128 v[8:11], v30 offset:48
	ds_read_b128 v[44:47], v30 offset:1024
	s_waitcnt lgkmcnt(4)
	v_mov_b32_e32 v53, v37
	v_lshlrev_b32_e32 v32, 16, v33
	s_add_i32 s5, s4, 0x818
	v_lshlrev_b32_e32 v16, 16, v17
	s_waitcnt lgkmcnt(0)
	v_mov_b32_e32 v52, v44
	v_mov_b32_e32 v44, v45
	v_mov_b32_e32 v45, v36
	v_pk_mov_b32 v[36:37], v[48:49], v[50:51] op_sel:[1,0]
	v_and_b32_e32 v17, 0xffff0000, v17
	v_pk_mul_f32 v[36:37], v[44:45], v[36:37]
	v_mov_b32_e32 v44, v46
	v_pk_fma_f32 v[36:37], v[52:53], v[50:51], v[36:37]
	v_mov_b32_e32 v46, v47
	v_pk_add_f32 v[28:29], v[28:29], v[36:37]
	v_and_b32_e32 v37, 0xffff0000, v33
	v_and_b32_e32 v36, 16, v33
	v_mov_b32_e32 v33, v37
	v_mov_b32_e32 v47, v38
	v_pk_mov_b32 v[36:37], v[36:37], v[32:33] op_sel:[1,0]
	v_mov_b32_e32 v45, v39
	v_pk_mul_f32 v[36:37], v[46:47], v[36:37]
	v_mov_b32_e32 v47, v41
	v_pk_fma_f32 v[32:33], v[44:45], v[32:33], v[36:37]
	ds_read_b128 v[36:39], v30 offset:1040
	v_pk_add_f32 v[28:29], v[28:29], v[32:33]
	v_and_b32_e32 v33, 0xffff0000, v34
	v_and_b32_e32 v32, 16, v34
	v_lshlrev_b32_e32 v44, 16, v34
	v_mov_b32_e32 v45, v33
	s_waitcnt lgkmcnt(0)
	v_mov_b32_e32 v46, v36
	v_mov_b32_e32 v36, v37
	v_mov_b32_e32 v37, v40
	v_pk_mov_b32 v[32:33], v[32:33], v[44:45] op_sel:[1,0]
	v_lshlrev_b32_e32 v34, 16, v35
	v_pk_mul_f32 v[32:33], v[36:37], v[32:33]
	v_mov_b32_e32 v36, v38
	v_pk_fma_f32 v[32:33], v[46:47], v[44:45], v[32:33]
	v_mov_b32_e32 v38, v39
	v_pk_add_f32 v[28:29], v[28:29], v[32:33]
	v_and_b32_e32 v33, 0xffff0000, v35
	v_and_b32_e32 v32, 16, v35
	v_mov_b32_e32 v35, v33
	v_mov_b32_e32 v39, v42
	v_pk_mov_b32 v[32:33], v[32:33], v[34:35] op_sel:[1,0]
	v_mov_b32_e32 v37, v43
	v_pk_mul_f32 v[32:33], v[38:39], v[32:33]
	s_nop 0
	v_pk_fma_f32 v[32:33], v[36:37], v[34:35], v[32:33]
	v_and_b32_e32 v36, 0xffff0000, v1
	v_pk_add_f32 v[28:29], v[28:29], v[32:33]
	v_mov_b32_e32 v32, s5
	ds_read2_b64 v[32:35], v32 offset1:1
	s_add_i32 s5, s4, 0x828
	v_lshlrev_b32_e32 v37, 16, v2
	s_add_i32 s4, s4, 64
	s_cmpk_gt_u32 s2, 0xf7
	s_waitcnt lgkmcnt(0)
	v_pk_mul_f32 v[16:17], v[32:33], v[16:17]
	s_nop 0
	v_add_f32_e32 v16, v16, v17
	v_add_f32_e32 v31, v31, v16
	v_lshlrev_b32_e32 v16, 16, v0
	v_and_b32_e32 v17, 0xffff0000, v0
	v_pk_mul_f32 v[16:17], v[34:35], v[16:17]
	s_nop 0
	v_add_f32_e32 v0, v16, v17
	v_add_f32_e32 v31, v31, v0
	v_mov_b32_e32 v0, s5
	ds_read2_b64 v[32:35], v0 offset1:1
	v_lshlrev_b32_e32 v0, 16, v1
	v_and_b32_e32 v1, 0xffff0000, v2
	s_waitcnt lgkmcnt(0)
	v_mov_b32_e32 v16, v33
	v_mov_b32_e32 v33, v35
	v_mov_b32_e32 v17, v34
	v_pk_mul_f32 v[0:1], v[32:33], v[0:1]
	ds_read_b128 v[32:35], v30 offset:1056
	v_pk_fma_f32 v[0:1], v[16:17], v[36:37], v[0:1]
	v_lshlrev_b32_e32 v16, 16, v4
	v_add_f32_e32 v0, v31, v0
	v_add_f32_e32 v31, v0, v1
	v_and_b32_e32 v1, 0xffff0000, v4
	v_and_b32_e32 v0, 16, v4
	v_mov_b32_e32 v17, v1
	s_waitcnt lgkmcnt(0)
	v_mov_b32_e32 v36, v32
	v_mov_b32_e32 v32, v33
	v_mov_b32_e32 v33, v12
	v_pk_mov_b32 v[0:1], v[0:1], v[16:17] op_sel:[1,0]
	v_mov_b32_e32 v37, v13
	v_pk_mul_f32 v[0:1], v[32:33], v[0:1]
	v_and_b32_e32 v13, 0xffff0000, v5
	v_pk_fma_f32 v[0:1], v[36:37], v[16:17], v[0:1]
	v_and_b32_e32 v12, 16, v5
	v_lshlrev_b32_e32 v4, 16, v5
	v_mov_b32_e32 v5, v13
	v_pk_add_f32 v[0:1], v[28:29], v[0:1]
	v_mov_b32_e32 v28, v35
	v_mov_b32_e32 v29, v14
	v_pk_mov_b32 v[12:13], v[12:13], v[4:5] op_sel:[1,0]
	v_mov_b32_e32 v16, v34
	v_mov_b32_e32 v17, v15
	v_pk_mul_f32 v[12:13], v[28:29], v[12:13]
	v_mov_b32_e32 v29, v9
	v_pk_fma_f32 v[4:5], v[16:17], v[4:5], v[12:13]
	ds_read_b128 v[12:15], v30 offset:1072
	v_pk_add_f32 v[0:1], v[0:1], v[4:5]
	v_and_b32_e32 v5, 0xffff0000, v6
	v_and_b32_e32 v4, 16, v6
	v_lshlrev_b32_e32 v16, 16, v6
	v_mov_b32_e32 v17, v5
	s_waitcnt lgkmcnt(0)
	v_mov_b32_e32 v28, v12
	v_mov_b32_e32 v12, v13
	v_mov_b32_e32 v13, v8
	v_pk_mov_b32 v[4:5], v[4:5], v[16:17] op_sel:[1,0]
	v_lshlrev_b32_e32 v6, 16, v7
	v_pk_mul_f32 v[4:5], v[12:13], v[4:5]
	v_mov_b32_e32 v12, v15
	v_pk_fma_f32 v[4:5], v[28:29], v[16:17], v[4:5]
	v_mov_b32_e32 v13, v10
	v_pk_add_f32 v[0:1], v[0:1], v[4:5]
	v_and_b32_e32 v5, 0xffff0000, v7
	v_and_b32_e32 v4, 16, v7
	v_mov_b32_e32 v7, v5
	v_pk_mov_b32 v[4:5], v[4:5], v[6:7] op_sel:[1,0]
	v_mov_b32_e32 v8, v14
	v_mov_b32_e32 v9, v11
	v_pk_mul_f32 v[4:5], v[12:13], v[4:5]
	s_nop 0
	v_pk_fma_f32 v[4:5], v[8:9], v[6:7], v[4:5]
	s_nop 0
	v_pk_add_f32 v[28:29], v[0:1], v[4:5]
	v_lshlrev_b32_e32 v0, 16, v3
	v_and_b32_e32 v1, 0xffff0000, v3
	ds_read_b64 v[2:3], v30 offset:2104
	s_waitcnt lgkmcnt(0)
	v_pk_mul_f32 v[0:1], v[2:3], v[0:1]
	s_nop 0
	v_add_f32_e32 v0, v0, v1
	v_add_f32_e32 v8, v31, v0
	s_waitcnt vmcnt(12)
	v_mov_b64_e32 v[4:5], v[60:61]
	v_mov_b64_e32 v[6:7], v[62:63]
	v_mov_b64_e32 v[32:33], v[64:65]
	v_mov_b64_e32 v[34:35], v[66:67]
	v_mov_b64_e32 v[0:1], v[68:69]
	v_mov_b64_e32 v[2:3], v[70:71]
	v_mov_b64_e32 v[14:15], v[72:73]
	v_mov_b64_e32 v[16:17], v[74:75]
	v_mov_b32_e32 v30, s4
	ds_read_b96 v[10:12], v30 offset:2048
	s_add_i32 s5, s4, 0x80c
	s_add_i32 s2, s2, 16
	v_lshl_add_u64 v[24:25], v[24:25], 0, 32
	v_lshl_add_u64 v[26:27], v[26:27], 0, 32
	global_load_dwordx4 v[60:63], v[24:25], off offset:96
	global_load_dwordx4 v[64:67], v[24:25], off offset:80
	global_load_dwordx4 v[68:71], v[26:27], off offset:96
	global_load_dwordx4 v[72:75], v[26:27], off offset:80
	v_and_b32_e32 v49, 0xffff0000, v32
	v_and_b32_e32 v48, 16, v32
	v_lshlrev_b32_e32 v36, 16, v14
	v_and_b32_e32 v37, 0xffff0000, v14
	s_waitcnt lgkmcnt(0)
	v_pk_mul_f32 v[10:11], v[10:11], v[36:37]
	v_lshlrev_b32_e32 v14, 16, v15
	v_add_f32_e32 v9, v10, v11
	v_add_f32_e32 v13, v8, v9
	ds_read_b32 v9, v30 offset:2068
	v_mov_b32_e32 v8, s5
	ds_read2_b32 v[36:37], v8 offset1:1
	v_and_b32_e32 v10, 0xffff0000, v15
	v_and_b32_e32 v15, 0xffff0000, v16
	v_mov_b32_e32 v8, v12
	v_lshlrev_b32_e32 v11, 16, v16
	s_waitcnt lgkmcnt(1)
	v_pk_mul_f32 v[8:9], v[8:9], v[14:15]
	v_lshlrev_b32_e32 v50, 16, v32
	s_waitcnt lgkmcnt(0)
	v_pk_fma_f32 v[8:9], v[36:37], v[10:11], v[8:9]
	v_mov_b32_e32 v51, v49
	v_add_f32_e32 v8, v13, v8
	v_add_f32_e32 v31, v8, v9
	ds_read_b128 v[36:39], v30
	ds_read_b128 v[40:43], v30 offset:16
	ds_read_b128 v[12:15], v30 offset:32
	ds_read_b128 v[8:11], v30 offset:48
	ds_read_b128 v[44:47], v30 offset:1024
	s_waitcnt lgkmcnt(4)
	v_mov_b32_e32 v53, v37
	v_lshlrev_b32_e32 v32, 16, v33
	s_add_i32 s5, s4, 0x818
	v_lshlrev_b32_e32 v16, 16, v17
	s_waitcnt lgkmcnt(0)
	v_mov_b32_e32 v52, v44
	v_mov_b32_e32 v44, v45
	v_mov_b32_e32 v45, v36
	v_pk_mov_b32 v[36:37], v[48:49], v[50:51] op_sel:[1,0]
	v_and_b32_e32 v17, 0xffff0000, v17
	v_pk_mul_f32 v[36:37], v[44:45], v[36:37]
	v_mov_b32_e32 v44, v46
	v_pk_fma_f32 v[36:37], v[52:53], v[50:51], v[36:37]
	v_mov_b32_e32 v46, v47
	v_pk_add_f32 v[28:29], v[28:29], v[36:37]
	v_and_b32_e32 v37, 0xffff0000, v33
	v_and_b32_e32 v36, 16, v33
	v_mov_b32_e32 v33, v37
	v_mov_b32_e32 v47, v38
	v_pk_mov_b32 v[36:37], v[36:37], v[32:33] op_sel:[1,0]
	v_mov_b32_e32 v45, v39
	v_pk_mul_f32 v[36:37], v[46:47], v[36:37]
	v_mov_b32_e32 v47, v41
	v_pk_fma_f32 v[32:33], v[44:45], v[32:33], v[36:37]
	ds_read_b128 v[36:39], v30 offset:1040
	v_pk_add_f32 v[28:29], v[28:29], v[32:33]
	v_and_b32_e32 v33, 0xffff0000, v34
	v_and_b32_e32 v32, 16, v34
	v_lshlrev_b32_e32 v44, 16, v34
	v_mov_b32_e32 v45, v33
	s_waitcnt lgkmcnt(0)
	v_mov_b32_e32 v46, v36
	v_mov_b32_e32 v36, v37
	v_mov_b32_e32 v37, v40
	v_pk_mov_b32 v[32:33], v[32:33], v[44:45] op_sel:[1,0]
	v_lshlrev_b32_e32 v34, 16, v35
	v_pk_mul_f32 v[32:33], v[36:37], v[32:33]
	v_mov_b32_e32 v36, v38
	v_pk_fma_f32 v[32:33], v[46:47], v[44:45], v[32:33]
	v_mov_b32_e32 v38, v39
	v_pk_add_f32 v[28:29], v[28:29], v[32:33]
	v_and_b32_e32 v33, 0xffff0000, v35
	v_and_b32_e32 v32, 16, v35
	v_mov_b32_e32 v35, v33
	v_mov_b32_e32 v39, v42
	v_pk_mov_b32 v[32:33], v[32:33], v[34:35] op_sel:[1,0]
	v_mov_b32_e32 v37, v43
	v_pk_mul_f32 v[32:33], v[38:39], v[32:33]
	s_nop 0
	v_pk_fma_f32 v[32:33], v[36:37], v[34:35], v[32:33]
	v_and_b32_e32 v36, 0xffff0000, v1
	v_pk_add_f32 v[28:29], v[28:29], v[32:33]
	v_mov_b32_e32 v32, s5
	ds_read2_b64 v[32:35], v32 offset1:1
	s_add_i32 s5, s4, 0x828
	v_lshlrev_b32_e32 v37, 16, v2
	s_add_i32 s4, s4, 64
	s_cmpk_gt_u32 s2, 0xf7
	s_waitcnt lgkmcnt(0)
	v_pk_mul_f32 v[16:17], v[32:33], v[16:17]
	s_nop 0
	v_add_f32_e32 v16, v16, v17
	v_add_f32_e32 v31, v31, v16
	v_lshlrev_b32_e32 v16, 16, v0
	v_and_b32_e32 v17, 0xffff0000, v0
	v_pk_mul_f32 v[16:17], v[34:35], v[16:17]
	s_nop 0
	v_add_f32_e32 v0, v16, v17
	v_add_f32_e32 v31, v31, v0
	v_mov_b32_e32 v0, s5
	ds_read2_b64 v[32:35], v0 offset1:1
	v_lshlrev_b32_e32 v0, 16, v1
	v_and_b32_e32 v1, 0xffff0000, v2
	s_waitcnt lgkmcnt(0)
	v_mov_b32_e32 v16, v33
	v_mov_b32_e32 v33, v35
	v_mov_b32_e32 v17, v34
	v_pk_mul_f32 v[0:1], v[32:33], v[0:1]
	ds_read_b128 v[32:35], v30 offset:1056
	v_pk_fma_f32 v[0:1], v[16:17], v[36:37], v[0:1]
	v_lshlrev_b32_e32 v16, 16, v4
	v_add_f32_e32 v0, v31, v0
	v_add_f32_e32 v31, v0, v1
	v_and_b32_e32 v1, 0xffff0000, v4
	v_and_b32_e32 v0, 16, v4
	v_mov_b32_e32 v17, v1
	s_waitcnt lgkmcnt(0)
	v_mov_b32_e32 v36, v32
	v_mov_b32_e32 v32, v33
	v_mov_b32_e32 v33, v12
	v_pk_mov_b32 v[0:1], v[0:1], v[16:17] op_sel:[1,0]
	v_mov_b32_e32 v37, v13
	v_pk_mul_f32 v[0:1], v[32:33], v[0:1]
	v_and_b32_e32 v13, 0xffff0000, v5
	v_pk_fma_f32 v[0:1], v[36:37], v[16:17], v[0:1]
	v_and_b32_e32 v12, 16, v5
	v_lshlrev_b32_e32 v4, 16, v5
	v_mov_b32_e32 v5, v13
	v_pk_add_f32 v[0:1], v[28:29], v[0:1]
	v_mov_b32_e32 v28, v35
	v_mov_b32_e32 v29, v14
	v_pk_mov_b32 v[12:13], v[12:13], v[4:5] op_sel:[1,0]
	v_mov_b32_e32 v16, v34
	v_mov_b32_e32 v17, v15
	v_pk_mul_f32 v[12:13], v[28:29], v[12:13]
	v_mov_b32_e32 v29, v9
	v_pk_fma_f32 v[4:5], v[16:17], v[4:5], v[12:13]
	ds_read_b128 v[12:15], v30 offset:1072
	v_pk_add_f32 v[0:1], v[0:1], v[4:5]
	v_and_b32_e32 v5, 0xffff0000, v6
	v_and_b32_e32 v4, 16, v6
	v_lshlrev_b32_e32 v16, 16, v6
	v_mov_b32_e32 v17, v5
	s_waitcnt lgkmcnt(0)
	v_mov_b32_e32 v28, v12
	v_mov_b32_e32 v12, v13
	v_mov_b32_e32 v13, v8
	v_pk_mov_b32 v[4:5], v[4:5], v[16:17] op_sel:[1,0]
	v_lshlrev_b32_e32 v6, 16, v7
	v_pk_mul_f32 v[4:5], v[12:13], v[4:5]
	v_mov_b32_e32 v12, v15
	v_pk_fma_f32 v[4:5], v[28:29], v[16:17], v[4:5]
	v_mov_b32_e32 v13, v10
	v_pk_add_f32 v[0:1], v[0:1], v[4:5]
	v_and_b32_e32 v5, 0xffff0000, v7
	v_and_b32_e32 v4, 16, v7
	v_mov_b32_e32 v7, v5
	v_pk_mov_b32 v[4:5], v[4:5], v[6:7] op_sel:[1,0]
	v_mov_b32_e32 v8, v14
	v_mov_b32_e32 v9, v11
	v_pk_mul_f32 v[4:5], v[12:13], v[4:5]
	s_nop 0
	v_pk_fma_f32 v[4:5], v[8:9], v[6:7], v[4:5]
	s_nop 0
	v_pk_add_f32 v[28:29], v[0:1], v[4:5]
	v_lshlrev_b32_e32 v0, 16, v3
	v_and_b32_e32 v1, 0xffff0000, v3
	ds_read_b64 v[2:3], v30 offset:2104
	s_waitcnt lgkmcnt(0)
	v_pk_mul_f32 v[0:1], v[2:3], v[0:1]
	s_nop 0
	v_add_f32_e32 v0, v0, v1
	v_add_f32_e32 v8, v31, v0
	s_cbranch_scc0 .LBB0_277
	s_waitcnt vmcnt(0)
	s_mov_b64 s[4:5], s[0:1]
	s_load_dwordx2 s[4:5], s[4:5], 0xa8
	s_waitcnt lgkmcnt(0)
	v_lshl_add_u64 v[0:1], v[22:23], 2, s[4:5]
	v_add_co_u32_e32 v0, vcc, 0x58500000, v0
	s_mov_b64 s[4:5], s[0:1]
	s_nop 0
	v_addc_co_u32_e32 v1, vcc, 0, v1, vcc
	global_store_dword v[0:1], v29, off
	s_load_dwordx2 s[4:5], s[4:5], 0xa8
	s_waitcnt lgkmcnt(0)
	v_lshl_add_u64 v[0:1], v[20:21], 2, s[4:5]
	v_add_co_u32_e32 v0, vcc, 0x58500000, v0
	s_mov_b64 s[4:5], s[0:1]
	s_nop 0
	v_addc_co_u32_e32 v1, vcc, 0, v1, vcc
	global_store_dword v[0:1], v28, off
	s_load_dwordx2 s[4:5], s[4:5], 0xa8
	s_waitcnt lgkmcnt(0)
	v_lshl_add_u64 v[0:1], v[18:19], 2, s[4:5]
	v_add_co_u32_e32 v0, vcc, 0x58500000, v0
	s_nop 1
	v_addc_co_u32_e32 v1, vcc, 0, v1, vcc
	global_store_dword v[0:1], v8, off
